# P3 alternating order keyed on blockIdx bit 3 instead of bit 8
# baseline (speedup 1.0000x reference)
.LBB0_326:
	s_or_b64 exec, exec, s[0:1]
	s_bitcmp1_b32 s89, 3
	s_cselect_b32 s0, 1, 0
	s_cmp_lg_u32 s26, 0x200
	s_cselect_b32 s0, 0, s0
	v_writelane_b32 v233, s0, 59
